# v023 + Swiglu epilogue: each group's broadcast wait moved to its first consumer (after two g*u products)
# baseline (speedup 1.0000x reference)
; __device__ __forceinline__ unsigned pk_bf16(float lo, float hi) { f32x2 v = {lo, hi}; bf16x2_t b = __builtin_convertvector(v, bf16x2_t); return __builtin_bit_cast(unsigned, b); }
; __device__ __forceinline__ float fast_exp2(float x) { return __builtin_amdgcn_exp2f(x); }
; __device__ __forceinline__ float fast_rcp(float x) { return __builtin_amdgcn_rcpf(x); }
;     __device__ __forceinline__ void operator()(const f32x4 (&acc)[2][2][4][2], const Unit& u, int wr, int wc, int fr, int fq, float rp0, float rp1, const f32x4& raw0, const f32x4& raw1, float& rn0, float& rn1) const {
;     ...
;         for (int k = 0; k < 8; ++k) rs[k] = __shfl((k >> 2) ? rp1 : rp0, fr + 16 * (k & 3));
; #pragma unroll
;         for (int ai = 0; ai < 2; ++ai)
; #pragma unroll
;             for (int m = 0; m < 4; ++m) {
;                 const int row = row0 + ai * HALF + m * 16; const float r = rs[ai * 4 + m];
;                 const float c1 = -1.4426950408889634f * r, r2 = r * r;
;                 const f32x4 ga = acc[ai][0][m][0], gb = acc[ai][0][m][1];
;                 const f32x4 ta = ga * c1, tb = gb * c1;
;                 f32x4 ea, eb;
; #pragma unroll
;                 for (int j = 0; j < 4; ++j) { ea[j] = fast_exp2(ta[j]); eb[j] = fast_exp2(tb[j]); }
;                 const f32x4 da = ea + 1.f, db = eb + 1.f;
;                 f32x4 qa, qb;
; #pragma unroll
;                 for (int j = 0; j < 4; ++j) { qa[j] = fast_rcp(da[j]); qb[j] = fast_rcp(db[j]); }
;                 const f32x4 oa = ((ga * acc[ai][1][m][0]) * r2) * qa, ob = ((gb * acc[ai][1][m][1]) * r2) * qb;
;                 u32x4 w;
;                 w.x = pk_bf16(oa[0], oa[1]); w.y = pk_bf16(oa[2], oa[3]); w.z = pk_bf16(ob[0], ob[1]); w.w = pk_bf16(ob[2], ob[3]);
;                 if (ai == 0 && m == 0) rstd_finish(raw0, raw1, rn0, rn1);
;                 *(u32x4*)(O + (size_t)row * FF + col0) = w;
.LBB0_322:
	s_andn2_b64 vcc, exec, s[4:5]
	s_mov_b64 s[4:5], -1
	v_and_or_b32 v157, v197, 64, v154
	v_lshlrev_b32_e32 v157, 2, v157
	ds_bpermute_b32 v162, v157, v144
	ds_bpermute_b32 v200, v157, v252
	ds_bpermute_b32 v163, v157, v144 offset:64
	ds_bpermute_b32 v202, v157, v252 offset:64
	ds_bpermute_b32 v164, v157, v144 offset:128
	ds_bpermute_b32 v204, v157, v252 offset:128
	ds_bpermute_b32 v165, v157, v144 offset:192
	ds_bpermute_b32 v206, v157, v252 offset:192
	ds_bpermute_b32 v166, v157, v145
	ds_bpermute_b32 v220, v157, v253
	ds_bpermute_b32 v167, v157, v145 offset:64
	ds_bpermute_b32 v222, v157, v253 offset:64
	ds_bpermute_b32 v168, v157, v145 offset:128
	ds_bpermute_b32 v224, v157, v253 offset:128
	ds_bpermute_b32 v169, v157, v145 offset:192
	ds_bpermute_b32 v226, v157, v253 offset:192
	v_lshl_add_u32 v153, s6, 8, v155
	v_lshl_or_b32 v160, s7, 7, v151
	v_mul_u32_u24_e32 v161, 0x1600, v153
	v_lshl_add_u32 v161, v160, 1, v161
	v_pk_mul_f32 v[126:127], v[118:119], v[126:127]
	v_pk_mul_f32 v[128:129], v[120:121], v[128:129]
	s_waitcnt lgkmcnt(14)
	v_mul_f32_e32 v228, 0xbfb8aa3b, v162
	v_pk_mul_f32 v[122:123], v[114:115], v[122:123]
	v_pk_mul_f32 v[124:125], v[116:117], v[124:125]
	v_pk_mul_f32 v[118:119], v[118:119], v[228:229] op_sel_hi:[1,0]
	v_pk_mul_f32 v[120:121], v[120:121], v[228:229] op_sel_hi:[1,0]
	v_pk_mul_f32 v[114:115], v[114:115], v[228:229] op_sel_hi:[1,0]
	v_pk_mul_f32 v[116:117], v[116:117], v[228:229] op_sel_hi:[1,0]
	v_exp_f32_e32 v118, v118
	v_exp_f32_e32 v119, v119
	v_exp_f32_e32 v120, v120
	v_exp_f32_e32 v121, v121
	v_exp_f32_e32 v114, v114
	v_exp_f32_e32 v115, v115
	v_exp_f32_e32 v116, v116
	v_exp_f32_e32 v117, v117
	v_pk_fma_f32 v[118:119], v[118:119], v[200:201], v[200:201] op_sel_hi:[1,0,0]
	v_pk_fma_f32 v[120:121], v[120:121], v[200:201], v[200:201] op_sel_hi:[1,0,0]
	v_pk_fma_f32 v[114:115], v[114:115], v[200:201], v[200:201] op_sel_hi:[1,0,0]
	v_pk_fma_f32 v[116:117], v[116:117], v[200:201], v[200:201] op_sel_hi:[1,0,0]
	v_rcp_f32_e32 v118, v118
	v_rcp_f32_e32 v119, v119
	v_rcp_f32_e32 v120, v120
	v_rcp_f32_e32 v121, v121
	v_rcp_f32_e32 v114, v114
	v_rcp_f32_e32 v115, v115
	v_rcp_f32_e32 v116, v116
	v_rcp_f32_e32 v117, v117
	v_pk_mul_f32 v[126:127], v[126:127], v[118:119]
	v_pk_mul_f32 v[128:129], v[128:129], v[120:121]
	v_pk_mul_f32 v[122:123], v[122:123], v[114:115]
	v_pk_mul_f32 v[124:125], v[124:125], v[116:117]
	v_cvt_pk_bf16_f32 v118, v126, v127
	v_cvt_pk_bf16_f32 v119, v128, v129
	v_cvt_pk_bf16_f32 v120, v122, v123
	v_cvt_pk_bf16_f32 v121, v124, v125
	global_store_dwordx4 v161, v[118:121], s[24:25]
	v_pk_mul_f32 v[110:111], v[102:103], v[110:111]
	v_pk_mul_f32 v[112:113], v[104:105], v[112:113]
	s_waitcnt lgkmcnt(12)
	v_mul_f32_e32 v228, 0xbfb8aa3b, v163
	v_pk_mul_f32 v[106:107], v[98:99], v[106:107]
	v_pk_mul_f32 v[108:109], v[100:101], v[108:109]
	v_pk_mul_f32 v[102:103], v[102:103], v[228:229] op_sel_hi:[1,0]
	v_pk_mul_f32 v[104:105], v[104:105], v[228:229] op_sel_hi:[1,0]
	v_pk_mul_f32 v[98:99], v[98:99], v[228:229] op_sel_hi:[1,0]
	v_pk_mul_f32 v[100:101], v[100:101], v[228:229] op_sel_hi:[1,0]
	v_exp_f32_e32 v102, v102
	v_exp_f32_e32 v103, v103
	v_exp_f32_e32 v104, v104
	v_exp_f32_e32 v105, v105
	v_exp_f32_e32 v98, v98
	v_exp_f32_e32 v99, v99
	v_exp_f32_e32 v100, v100
	v_exp_f32_e32 v101, v101
	v_pk_fma_f32 v[102:103], v[102:103], v[202:203], v[202:203] op_sel_hi:[1,0,0]
	v_pk_fma_f32 v[104:105], v[104:105], v[202:203], v[202:203] op_sel_hi:[1,0,0]
	v_pk_fma_f32 v[98:99], v[98:99], v[202:203], v[202:203] op_sel_hi:[1,0,0]
	v_pk_fma_f32 v[100:101], v[100:101], v[202:203], v[202:203] op_sel_hi:[1,0,0]
	v_rcp_f32_e32 v102, v102
	v_rcp_f32_e32 v103, v103
	v_rcp_f32_e32 v104, v104
	v_rcp_f32_e32 v105, v105
	v_rcp_f32_e32 v98, v98
	v_rcp_f32_e32 v99, v99
	v_rcp_f32_e32 v100, v100
	v_rcp_f32_e32 v101, v101
	v_pk_mul_f32 v[110:111], v[110:111], v[102:103]
	v_pk_mul_f32 v[112:113], v[112:113], v[104:105]
	v_pk_mul_f32 v[106:107], v[106:107], v[98:99]
	v_pk_mul_f32 v[108:109], v[108:109], v[100:101]
	v_cvt_pk_bf16_f32 v102, v110, v111
	v_cvt_pk_bf16_f32 v103, v112, v113
	v_cvt_pk_bf16_f32 v104, v106, v107
	v_cvt_pk_bf16_f32 v105, v108, v109
	v_add_u32_e32 v170, 0x16000, v161
	global_store_dwordx4 v170, v[102:105], s[24:25]
	v_pk_mul_f32 v[94:95], v[86:87], v[94:95]
	v_pk_mul_f32 v[96:97], v[88:89], v[96:97]
	s_waitcnt lgkmcnt(10)
	v_mul_f32_e32 v228, 0xbfb8aa3b, v164
	v_pk_mul_f32 v[90:91], v[82:83], v[90:91]
	v_pk_mul_f32 v[92:93], v[84:85], v[92:93]
	v_pk_mul_f32 v[86:87], v[86:87], v[228:229] op_sel_hi:[1,0]
	v_pk_mul_f32 v[88:89], v[88:89], v[228:229] op_sel_hi:[1,0]
	v_pk_mul_f32 v[82:83], v[82:83], v[228:229] op_sel_hi:[1,0]
	v_pk_mul_f32 v[84:85], v[84:85], v[228:229] op_sel_hi:[1,0]
	v_exp_f32_e32 v86, v86
	v_exp_f32_e32 v87, v87
	v_exp_f32_e32 v88, v88
	v_exp_f32_e32 v89, v89
	v_exp_f32_e32 v82, v82
	v_exp_f32_e32 v83, v83
	v_exp_f32_e32 v84, v84
	v_exp_f32_e32 v85, v85
	v_pk_fma_f32 v[86:87], v[86:87], v[204:205], v[204:205] op_sel_hi:[1,0,0]
	v_pk_fma_f32 v[88:89], v[88:89], v[204:205], v[204:205] op_sel_hi:[1,0,0]
	v_pk_fma_f32 v[82:83], v[82:83], v[204:205], v[204:205] op_sel_hi:[1,0,0]
	v_pk_fma_f32 v[84:85], v[84:85], v[204:205], v[204:205] op_sel_hi:[1,0,0]
	v_rcp_f32_e32 v86, v86
	v_rcp_f32_e32 v87, v87
	v_rcp_f32_e32 v88, v88
	v_rcp_f32_e32 v89, v89
	v_rcp_f32_e32 v82, v82
	v_rcp_f32_e32 v83, v83
	v_rcp_f32_e32 v84, v84
	v_rcp_f32_e32 v85, v85
	v_pk_mul_f32 v[94:95], v[94:95], v[86:87]
	v_pk_mul_f32 v[96:97], v[96:97], v[88:89]
	v_pk_mul_f32 v[90:91], v[90:91], v[82:83]
	v_pk_mul_f32 v[92:93], v[92:93], v[84:85]
	v_cvt_pk_bf16_f32 v86, v94, v95
	v_cvt_pk_bf16_f32 v87, v96, v97
	v_cvt_pk_bf16_f32 v88, v90, v91
	v_cvt_pk_bf16_f32 v89, v92, v93
	v_add_u32_e32 v170, 0x2c000, v161
	global_store_dwordx4 v170, v[86:89], s[24:25]
	v_pk_mul_f32 v[78:79], v[70:71], v[78:79]
	v_pk_mul_f32 v[80:81], v[72:73], v[80:81]
	s_waitcnt lgkmcnt(8)
; __device__ __forceinline__ unsigned pk_bf16(float lo, float hi) { f32x2 v = {lo, hi}; bf16x2_t b = __builtin_convertvector(v, bf16x2_t); return __builtin_bit_cast(unsigned, b); }
; __device__ __forceinline__ float fast_exp2(float x) { return __builtin_amdgcn_exp2f(x); }
; __device__ __forceinline__ float fast_rcp(float x) { return __builtin_amdgcn_rcpf(x); }
;     __device__ __forceinline__ void operator()(const f32x4 (&acc)[2][2][4][2], const Unit& u, int wr, int wc, int fr, int fq, float rp0, float rp1, const f32x4& raw0, const f32x4& raw1, float& rn0, float& rn1) const {
;     ...
;                 const int row = row0 + ai * HALF + m * 16; const float r = rs[ai * 4 + m];
;                 const float c1 = -1.4426950408889634f * r, r2 = r * r;
;                 const f32x4 ga = acc[ai][0][m][0], gb = acc[ai][0][m][1];
;                 const f32x4 ta = ga * c1, tb = gb * c1;
;                 f32x4 ea, eb;
; #pragma unroll
;                 for (int j = 0; j < 4; ++j) { ea[j] = fast_exp2(ta[j]); eb[j] = fast_exp2(tb[j]); }
;                 const f32x4 da = ea + 1.f, db = eb + 1.f;
;                 f32x4 qa, qb;
; #pragma unroll
;                 for (int j = 0; j < 4; ++j) { qa[j] = fast_rcp(da[j]); qb[j] = fast_rcp(db[j]); }
;                 const f32x4 oa = ((ga * acc[ai][1][m][0]) * r2) * qa, ob = ((gb * acc[ai][1][m][1]) * r2) * qb;
;                 u32x4 w;
;                 w.x = pk_bf16(oa[0], oa[1]); w.y = pk_bf16(oa[2], oa[3]); w.z = pk_bf16(ob[0], ob[1]); w.w = pk_bf16(ob[2], ob[3]);
;                 if (ai == 0 && m == 0) rstd_finish(raw0, raw1, rn0, rn1);
;                 *(u32x4*)(O + (size_t)row * FF + col0) = w;
	v_mul_f32_e32 v228, 0xbfb8aa3b, v165
	v_pk_mul_f32 v[74:75], v[62:63], v[74:75]
	v_pk_mul_f32 v[76:77], v[64:65], v[76:77]
	v_pk_mul_f32 v[70:71], v[70:71], v[228:229] op_sel_hi:[1,0]
	v_pk_mul_f32 v[72:73], v[72:73], v[228:229] op_sel_hi:[1,0]
	v_pk_mul_f32 v[62:63], v[62:63], v[228:229] op_sel_hi:[1,0]
	v_pk_mul_f32 v[64:65], v[64:65], v[228:229] op_sel_hi:[1,0]
	v_exp_f32_e32 v70, v70
	v_exp_f32_e32 v71, v71
	v_exp_f32_e32 v72, v72
	v_exp_f32_e32 v73, v73
	v_exp_f32_e32 v62, v62
	v_exp_f32_e32 v63, v63
	v_exp_f32_e32 v64, v64
	v_exp_f32_e32 v65, v65
	v_pk_fma_f32 v[70:71], v[70:71], v[206:207], v[206:207] op_sel_hi:[1,0,0]
	v_pk_fma_f32 v[72:73], v[72:73], v[206:207], v[206:207] op_sel_hi:[1,0,0]
	v_pk_fma_f32 v[62:63], v[62:63], v[206:207], v[206:207] op_sel_hi:[1,0,0]
	v_pk_fma_f32 v[64:65], v[64:65], v[206:207], v[206:207] op_sel_hi:[1,0,0]
	v_rcp_f32_e32 v70, v70
	v_rcp_f32_e32 v71, v71
	v_rcp_f32_e32 v72, v72
	v_rcp_f32_e32 v73, v73
	v_rcp_f32_e32 v62, v62
	v_rcp_f32_e32 v63, v63
	v_rcp_f32_e32 v64, v64
	v_rcp_f32_e32 v65, v65
	v_pk_mul_f32 v[78:79], v[78:79], v[70:71]
	v_pk_mul_f32 v[80:81], v[80:81], v[72:73]
	v_pk_mul_f32 v[74:75], v[74:75], v[62:63]
	v_pk_mul_f32 v[76:77], v[76:77], v[64:65]
	v_cvt_pk_bf16_f32 v70, v78, v79
	v_cvt_pk_bf16_f32 v71, v80, v81
	v_cvt_pk_bf16_f32 v72, v74, v75
	v_cvt_pk_bf16_f32 v73, v76, v77
	v_add_u32_e32 v170, 0x42000, v161
	global_store_dwordx4 v170, v[70:73], s[24:25]
	v_pk_mul_f32 v[66:67], v[54:55], v[66:67]
	v_pk_mul_f32 v[68:69], v[56:57], v[68:69]
	s_waitcnt lgkmcnt(6)
	v_mul_f32_e32 v228, 0xbfb8aa3b, v166
	v_pk_mul_f32 v[58:59], v[50:51], v[58:59]
	v_pk_mul_f32 v[60:61], v[52:53], v[60:61]
	v_pk_mul_f32 v[54:55], v[54:55], v[228:229] op_sel_hi:[1,0]
	v_pk_mul_f32 v[56:57], v[56:57], v[228:229] op_sel_hi:[1,0]
	v_pk_mul_f32 v[50:51], v[50:51], v[228:229] op_sel_hi:[1,0]
	v_pk_mul_f32 v[52:53], v[52:53], v[228:229] op_sel_hi:[1,0]
	v_exp_f32_e32 v54, v54
	v_exp_f32_e32 v55, v55
	v_exp_f32_e32 v56, v56
	v_exp_f32_e32 v57, v57
	v_exp_f32_e32 v50, v50
	v_exp_f32_e32 v51, v51
	v_exp_f32_e32 v52, v52
	v_exp_f32_e32 v53, v53
	v_pk_fma_f32 v[54:55], v[54:55], v[220:221], v[220:221] op_sel_hi:[1,0,0]
	v_pk_fma_f32 v[56:57], v[56:57], v[220:221], v[220:221] op_sel_hi:[1,0,0]
	v_pk_fma_f32 v[50:51], v[50:51], v[220:221], v[220:221] op_sel_hi:[1,0,0]
	v_pk_fma_f32 v[52:53], v[52:53], v[220:221], v[220:221] op_sel_hi:[1,0,0]
	v_rcp_f32_e32 v54, v54
	v_rcp_f32_e32 v55, v55
	v_rcp_f32_e32 v56, v56
	v_rcp_f32_e32 v57, v57
	v_rcp_f32_e32 v50, v50
	v_rcp_f32_e32 v51, v51
	v_rcp_f32_e32 v52, v52
	v_rcp_f32_e32 v53, v53
	v_pk_mul_f32 v[66:67], v[66:67], v[54:55]
	v_pk_mul_f32 v[68:69], v[68:69], v[56:57]
	v_pk_mul_f32 v[58:59], v[58:59], v[50:51]
	v_pk_mul_f32 v[60:61], v[60:61], v[52:53]
	v_cvt_pk_bf16_f32 v54, v66, v67
	v_cvt_pk_bf16_f32 v55, v68, v69
	v_cvt_pk_bf16_f32 v56, v58, v59
	v_cvt_pk_bf16_f32 v57, v60, v61
	v_add_u32_e32 v170, 0xb0000, v161
	global_store_dwordx4 v170, v[54:57], s[24:25]
	v_pk_mul_f32 v[46:47], v[38:39], v[46:47]
	v_pk_mul_f32 v[48:49], v[40:41], v[48:49]
	s_waitcnt lgkmcnt(4)
	v_mul_f32_e32 v228, 0xbfb8aa3b, v167
	v_pk_mul_f32 v[42:43], v[34:35], v[42:43]
	v_pk_mul_f32 v[44:45], v[36:37], v[44:45]
	v_pk_mul_f32 v[38:39], v[38:39], v[228:229] op_sel_hi:[1,0]
	v_pk_mul_f32 v[40:41], v[40:41], v[228:229] op_sel_hi:[1,0]
	v_pk_mul_f32 v[34:35], v[34:35], v[228:229] op_sel_hi:[1,0]
	v_pk_mul_f32 v[36:37], v[36:37], v[228:229] op_sel_hi:[1,0]
	v_exp_f32_e32 v38, v38
	v_exp_f32_e32 v39, v39
	v_exp_f32_e32 v40, v40
	v_exp_f32_e32 v41, v41
	v_exp_f32_e32 v34, v34
	v_exp_f32_e32 v35, v35
	v_exp_f32_e32 v36, v36
	v_exp_f32_e32 v37, v37
	v_pk_fma_f32 v[38:39], v[38:39], v[222:223], v[222:223] op_sel_hi:[1,0,0]
	v_pk_fma_f32 v[40:41], v[40:41], v[222:223], v[222:223] op_sel_hi:[1,0,0]
	v_pk_fma_f32 v[34:35], v[34:35], v[222:223], v[222:223] op_sel_hi:[1,0,0]
	v_pk_fma_f32 v[36:37], v[36:37], v[222:223], v[222:223] op_sel_hi:[1,0,0]
	v_rcp_f32_e32 v38, v38
	v_rcp_f32_e32 v39, v39
	v_rcp_f32_e32 v40, v40
	v_rcp_f32_e32 v41, v41
	v_rcp_f32_e32 v34, v34
	v_rcp_f32_e32 v35, v35
	v_rcp_f32_e32 v36, v36
	v_rcp_f32_e32 v37, v37
	v_pk_mul_f32 v[46:47], v[46:47], v[38:39]
	v_pk_mul_f32 v[48:49], v[48:49], v[40:41]
	v_pk_mul_f32 v[42:43], v[42:43], v[34:35]
	v_pk_mul_f32 v[44:45], v[44:45], v[36:37]
	v_cvt_pk_bf16_f32 v38, v46, v47
	v_cvt_pk_bf16_f32 v39, v48, v49
	v_cvt_pk_bf16_f32 v40, v42, v43
	v_cvt_pk_bf16_f32 v41, v44, v45
	v_add_u32_e32 v170, 0xc6000, v161
	global_store_dwordx4 v170, v[38:41], s[24:25]
	v_pk_mul_f32 v[30:31], v[22:23], v[30:31]
	v_pk_mul_f32 v[32:33], v[24:25], v[32:33]
	s_waitcnt lgkmcnt(2)
; __device__ __forceinline__ unsigned pk_bf16(float lo, float hi) { f32x2 v = {lo, hi}; bf16x2_t b = __builtin_convertvector(v, bf16x2_t); return __builtin_bit_cast(unsigned, b); }
; __device__ __forceinline__ float fast_exp2(float x) { return __builtin_amdgcn_exp2f(x); }
; __device__ __forceinline__ float fast_rcp(float x) { return __builtin_amdgcn_rcpf(x); }
; __device__ __forceinline__ void rstd_finish(const f32x4& raw0, const f32x4& raw1, float& rn0, float& rn1) {
;     rn0 = rsqrtf(((raw0.x + raw0.y) + (raw0.z + raw0.w)) * (1.f / DM) + EPS); rn1 = rsqrtf(((raw1.x + raw1.y) + (raw1.z + raw1.w)) * (1.f / DM) + EPS);
;     asm volatile("" :: "v"(rn0), "v"(rn1) : "memory");
;     __device__ __forceinline__ void operator()(const f32x4 (&acc)[2][2][4][2], const Unit& u, int wr, int wc, int fr, int fq, float rp0, float rp1, const f32x4& raw0, const f32x4& raw1, float& rn0, float& rn1) const {
;     ...
;                 const int row = row0 + ai * HALF + m * 16; const float r = rs[ai * 4 + m];
;                 const float c1 = -1.4426950408889634f * r, r2 = r * r;
;                 const f32x4 ga = acc[ai][0][m][0], gb = acc[ai][0][m][1];
;                 const f32x4 ta = ga * c1, tb = gb * c1;
;                 f32x4 ea, eb;
; #pragma unroll
;                 for (int j = 0; j < 4; ++j) { ea[j] = fast_exp2(ta[j]); eb[j] = fast_exp2(tb[j]); }
;                 const f32x4 da = ea + 1.f, db = eb + 1.f;
;                 f32x4 qa, qb;
; #pragma unroll
;                 for (int j = 0; j < 4; ++j) { qa[j] = fast_rcp(da[j]); qb[j] = fast_rcp(db[j]); }
;                 const f32x4 oa = ((ga * acc[ai][1][m][0]) * r2) * qa, ob = ((gb * acc[ai][1][m][1]) * r2) * qb;
;                 u32x4 w;
;                 w.x = pk_bf16(oa[0], oa[1]); w.y = pk_bf16(oa[2], oa[3]); w.z = pk_bf16(ob[0], ob[1]); w.w = pk_bf16(ob[2], ob[3]);
;                 if (ai == 0 && m == 0) rstd_finish(raw0, raw1, rn0, rn1);
;                 *(u32x4*)(O + (size_t)row * FF + col0) = w;
	v_mul_f32_e32 v228, 0xbfb8aa3b, v168
	v_pk_mul_f32 v[26:27], v[18:19], v[26:27]
	v_pk_mul_f32 v[28:29], v[20:21], v[28:29]
	v_pk_mul_f32 v[22:23], v[22:23], v[228:229] op_sel_hi:[1,0]
	v_pk_mul_f32 v[24:25], v[24:25], v[228:229] op_sel_hi:[1,0]
	v_pk_mul_f32 v[18:19], v[18:19], v[228:229] op_sel_hi:[1,0]
	v_pk_mul_f32 v[20:21], v[20:21], v[228:229] op_sel_hi:[1,0]
	v_exp_f32_e32 v22, v22
	v_exp_f32_e32 v23, v23
	v_exp_f32_e32 v24, v24
	v_exp_f32_e32 v25, v25
	v_exp_f32_e32 v18, v18
	v_exp_f32_e32 v19, v19
	v_exp_f32_e32 v20, v20
	v_exp_f32_e32 v21, v21
	v_pk_fma_f32 v[22:23], v[22:23], v[224:225], v[224:225] op_sel_hi:[1,0,0]
	v_pk_fma_f32 v[24:25], v[24:25], v[224:225], v[224:225] op_sel_hi:[1,0,0]
	v_pk_fma_f32 v[18:19], v[18:19], v[224:225], v[224:225] op_sel_hi:[1,0,0]
	v_pk_fma_f32 v[20:21], v[20:21], v[224:225], v[224:225] op_sel_hi:[1,0,0]
	v_rcp_f32_e32 v22, v22
	v_rcp_f32_e32 v23, v23
	v_rcp_f32_e32 v24, v24
	v_rcp_f32_e32 v25, v25
	v_rcp_f32_e32 v18, v18
	v_rcp_f32_e32 v19, v19
	v_rcp_f32_e32 v20, v20
	v_rcp_f32_e32 v21, v21
	v_pk_mul_f32 v[30:31], v[30:31], v[22:23]
	v_pk_mul_f32 v[32:33], v[32:33], v[24:25]
	v_pk_mul_f32 v[26:27], v[26:27], v[18:19]
	v_pk_mul_f32 v[28:29], v[28:29], v[20:21]
	v_cvt_pk_bf16_f32 v22, v30, v31
	v_cvt_pk_bf16_f32 v23, v32, v33
	v_cvt_pk_bf16_f32 v24, v26, v27
	v_cvt_pk_bf16_f32 v25, v28, v29
	v_add_u32_e32 v170, 0xdc000, v161
	global_store_dwordx4 v170, v[22:25], s[24:25]
	v_pk_mul_f32 v[14:15], v[6:7], v[14:15]
	v_pk_mul_f32 v[16:17], v[8:9], v[16:17]
	s_waitcnt lgkmcnt(0)
	v_mul_f32_e32 v228, 0xbfb8aa3b, v169
	v_pk_mul_f32 v[10:11], v[2:3], v[10:11]
	v_pk_mul_f32 v[12:13], v[4:5], v[12:13]
	v_pk_mul_f32 v[6:7], v[6:7], v[228:229] op_sel_hi:[1,0]
	v_pk_mul_f32 v[8:9], v[8:9], v[228:229] op_sel_hi:[1,0]
	v_pk_mul_f32 v[2:3], v[2:3], v[228:229] op_sel_hi:[1,0]
	v_pk_mul_f32 v[4:5], v[4:5], v[228:229] op_sel_hi:[1,0]
	v_exp_f32_e32 v6, v6
	v_exp_f32_e32 v7, v7
	v_exp_f32_e32 v8, v8
	v_exp_f32_e32 v9, v9
	v_exp_f32_e32 v2, v2
	v_exp_f32_e32 v3, v3
	v_exp_f32_e32 v4, v4
	v_exp_f32_e32 v5, v5
	v_pk_fma_f32 v[6:7], v[6:7], v[226:227], v[226:227] op_sel_hi:[1,0,0]
	v_pk_fma_f32 v[8:9], v[8:9], v[226:227], v[226:227] op_sel_hi:[1,0,0]
	v_pk_fma_f32 v[2:3], v[2:3], v[226:227], v[226:227] op_sel_hi:[1,0,0]
	v_pk_fma_f32 v[4:5], v[4:5], v[226:227], v[226:227] op_sel_hi:[1,0,0]
	v_rcp_f32_e32 v6, v6
	v_rcp_f32_e32 v7, v7
	v_rcp_f32_e32 v8, v8
	v_rcp_f32_e32 v9, v9
	v_rcp_f32_e32 v2, v2
	v_rcp_f32_e32 v3, v3
	v_rcp_f32_e32 v4, v4
	v_rcp_f32_e32 v5, v5
	v_pk_mul_f32 v[14:15], v[14:15], v[6:7]
	v_pk_mul_f32 v[16:17], v[16:17], v[8:9]
	v_pk_mul_f32 v[10:11], v[10:11], v[2:3]
	v_pk_mul_f32 v[12:13], v[12:13], v[4:5]
	v_cvt_pk_bf16_f32 v6, v14, v15
	v_cvt_pk_bf16_f32 v7, v16, v17
	v_cvt_pk_bf16_f32 v8, v10, v11
	v_cvt_pk_bf16_f32 v9, v12, v13
	v_add_u32_e32 v170, 0xf2000, v161
	global_store_dwordx4 v170, v[6:9], s[24:25]
	s_waitcnt vmcnt(8)
	v_mov_b32_e32 v122, v135
	v_mov_b32_e32 v123, v136
	v_mov_b32_e32 v135, v137
	v_mov_b32_e32 v124, v131
	v_mov_b32_e32 v125, v132
	v_mov_b32_e32 v131, v133
	v_pk_add_f32 v[122:123], v[122:123], v[134:135]
	v_pk_add_f32 v[124:125], v[124:125], v[130:131]
	v_mov_b32_e32 v126, v124
	v_mov_b32_e32 v127, v122
	v_mov_b32_e32 v122, v125
	v_pk_add_f32 v[122:123], v[126:127], v[122:123]
	v_pk_fma_f32 v[122:123], v[122:123], s[84:85], v[182:183] op_sel_hi:[1,0,0]
	v_mov_b32_e32 v252, v122
	v_mov_b32_e32 v253, v123
	v_mul_f32_e32 v119, 0x4b800000, v123
	v_mul_f32_e32 v118, 0x4b800000, v122
	v_cmp_gt_f32_e64 s[100:101], s89, v123
	v_cmp_gt_f32_e64 s[6:7], s89, v122
	s_nop 1
	v_cndmask_b32_e64 v119, v123, v119, s[100:101]
	v_cndmask_b32_e64 v118, v122, v118, s[6:7]
	v_rsq_f32_e32 v123, v119
	v_rsq_f32_e32 v122, v118
	s_nop 0
	v_pk_mul_f32 v[120:121], v[122:123], s[78:79] op_sel_hi:[1,0]
	v_cndmask_b32_e64 v145, v123, v121, s[100:101]
	v_cndmask_b32_e64 v144, v122, v120, s[6:7]
	s_cbranch_vccnz .LBB0_315
	s_andn2_b64 vcc, exec, s[2:3]
	s_cbranch_vccnz .LBB0_314
	s_barrier
	s_branch .LBB0_314
